# v044 minus the 12 back-to-back s_setprio 0/1 pairs in the middle of the GEMM MMA blocks (A/B of hipcc's mid-block priority flips)
# baseline (speedup 1.0000x reference)
; #define PG8_STAGE(bufoff, gbase, voff) do { _Pragma("unroll") for (int _i = 0; _i < 2; ++_i) \
;         __builtin_amdgcn_global_load_lds((const unsigned*)((const char*)(gbase) + (voff)[_i]), (PG8_LAS unsigned*)(lds + (bufoff) + ldsw + _i * 8192), 16, 0, 0); } while (0)
; #define PG8_LDA(dst, b, h) do { _Pragma("unroll") for (int m = 0; m < 4; ++m) _Pragma("unroll") for (int k = 0; k < 2; ++k) dst[m][k] = *(const PG8_LAS bf16x8*)(lds + PG8_SA(b, h) + aoff + m * 2048 + k * 1024); } while (0)
; #define PG8_LDB(dst, b, h) do { _Pragma("unroll") for (int n = 0; n < 2; ++n) _Pragma("unroll") for (int k = 0; k < 2; ++k) dst[n][k] = *(const PG8_LAS bf16x8*)(lds + PG8_SB(b, h) + boff + n * 2048 + k * 1024); } while (0)
; #define PG8_MMA(ai, bj, At, Bt) do { __builtin_amdgcn_s_setprio(1); _Pragma("unroll") for (int m = 0; m < 4; ++m) _Pragma("unroll") for (int n = 0; n < 2; ++n) _Pragma("unroll") for (int k = 0; k < 2; ++k) \
;         acc[ai][bj][m][n] = __builtin_amdgcn_mfma_f32_16x16x32_bf16(Bt[n][k], At[m][k], acc[ai][bj][m][n], 0, 0, 0); __builtin_amdgcn_s_setprio(0); } while (0)
; #define PG8_WAIT_V(n) asm volatile("s_waitcnt vmcnt(" #n ")" ::: "memory")
; #define PG8_WAIT_L(n) asm volatile("s_waitcnt lgkmcnt(" #n ")" ::: "memory")
; template <class Epi, class Sched, bool ALIGN_EPI = false, bool SP2 = false>
; __device__ __forceinline__ void gemm_phase(PG8_LAS unsigned char* lds, const Gemm g, const Sched& S, const Epi& E) {
;     ...
;             const bool last = (t == nt - 2);
;             const char* a1 = cA + (size_t)(t + 1) * kstep;
;             const char* a2 = last ? nA : cA + (size_t)(t + 2) * kstep; const char* b2 = last ? nB : cB + (size_t)(t + 2) * kstep;
;             const char* a3 = a2 + kstep; const char* b3 = b2 + kstep;
;             if (last && has_next) S.a_ready(nxt);
;             if constexpr (SP2) {
;             PG8_LDB(B0, 0, 0); PG8_LDB(B1, 0, 1); PG8_SCHED; PG8_LDA(At, 0, 0); PG8_STAGE(PG8_SA(1, 1), a1 + hstep, voffA);
;             PG8_WAIT_V(8); PG8_WAIT_L(0); PG8_BAR; PG8_MMA(0, 0, At, B0); PG8_MMA(0, 1, At, B1); PG8_BAR; PG8_SCHED;
;             PG8_LDA(At, 0, 1); PG8_STAGE(PG8_SB(0, 0), b2, voffB); PG8_STAGE(PG8_SB(0, 1), b2 + hstep, voffB); PG8_STAGE(PG8_SA(0, 0), a2, voffA);
;             PG8_WAIT_V(8); PG8_WAIT_L(0); PG8_BAR; PG8_MMA(1, 0, At, B0); PG8_MMA(1, 1, At, B1); PG8_BAR; PG8_SCHED;
.LBB0_117:
	s_add_u32 s50, s48, 0xfff80080
	s_addc_u32 s51, s49, -1
	s_add_i32 s61, 0, 0x10000
	s_cmp_eq_u32 s58, 28
	s_cselect_b32 s77, s1, s51
	s_cselect_b32 s76, s24, s50
	v_add_u32_e32 v0, s61, v234
	s_cselect_b32 s51, s25, s47
	s_cselect_b32 s50, s38, s39
	s_add_i32 s63, 0, 0x14000
	ds_read_b128 v[124:127], v0
	ds_read_b128 v[128:131], v0 offset:1024
	ds_read_b128 v[132:135], v0 offset:2048
	ds_read_b128 v[140:143], v0 offset:3072
	v_add_u32_e32 v0, s63, v234
	ds_read_b128 v[148:151], v0
	ds_read_b128 v[152:155], v0 offset:1024
	ds_read_b128 v[156:159], v0 offset:2048
	ds_read_b128 v[160:163], v0 offset:3072
	v_lshl_add_u64 v[2:3], s[48:49], 0, v[192:193]
	s_add_i32 m0, s82, 0xc000
	ds_read_b128 v[164:167], v235
	ds_read_b128 v[198:201], v235 offset:1024
	ds_read_b128 v[202:205], v235 offset:2048
	ds_read_b128 v[206:209], v235 offset:3072
	ds_read_b128 v[210:213], v235 offset:4096
	ds_read_b128 v[214:217], v235 offset:5120
	ds_read_b128 v[218:221], v235 offset:6144
	ds_read_b128 v[236:239], v235 offset:7168
	global_load_lds_dwordx4 v[2:3], off
	v_lshl_add_u64 v[2:3], s[48:49], 0, v[194:195]
	s_add_i32 m0, s82, 0xe000
	s_nop 0
	global_load_lds_dwordx4 v[2:3], off
	s_waitcnt vmcnt(8)
	s_waitcnt lgkmcnt(0)
	s_barrier
	s_setprio 1
	s_waitcnt lgkmcnt(0)
	v_mfma_f32_16x16x32_bf16 v[144:147], v[124:127], v[164:167], v[144:147]
	v_mfma_f32_16x16x32_bf16 v[136:139], v[132:135], v[164:167], v[136:139]
	v_mfma_f32_16x16x32_bf16 v[112:115], v[124:127], v[202:205], v[112:115]
	v_mfma_f32_16x16x32_bf16 v[108:111], v[132:135], v[202:205], v[108:111]
	v_mfma_f32_16x16x32_bf16 v[96:99], v[124:127], v[210:213], v[96:99]
	v_mfma_f32_16x16x32_bf16 v[92:95], v[132:135], v[210:213], v[92:95]
	v_mfma_f32_16x16x32_bf16 v[80:83], v[124:127], v[218:221], v[80:83]
	v_mfma_f32_16x16x32_bf16 v[76:79], v[132:135], v[218:221], v[76:79]
	v_mfma_f32_16x16x32_bf16 v[144:147], v[128:131], v[198:201], v[144:147]
	v_mfma_f32_16x16x32_bf16 v[136:139], v[140:143], v[198:201], v[136:139]
	v_mfma_f32_16x16x32_bf16 v[112:115], v[128:131], v[206:209], v[112:115]
	v_mfma_f32_16x16x32_bf16 v[108:111], v[140:143], v[206:209], v[108:111]
	v_mfma_f32_16x16x32_bf16 v[96:99], v[128:131], v[214:217], v[96:99]
	v_mfma_f32_16x16x32_bf16 v[92:95], v[140:143], v[214:217], v[92:95]
	v_mfma_f32_16x16x32_bf16 v[80:83], v[128:131], v[236:239], v[80:83]
	v_mfma_f32_16x16x32_bf16 v[76:79], v[140:143], v[236:239], v[76:79]
	v_mfma_f32_16x16x32_bf16 v[120:123], v[148:151], v[164:167], v[120:123]
	v_mfma_f32_16x16x32_bf16 v[116:119], v[156:159], v[164:167], v[116:119]
	v_mfma_f32_16x16x32_bf16 v[104:107], v[148:151], v[202:205], v[104:107]
	v_mfma_f32_16x16x32_bf16 v[100:103], v[156:159], v[202:205], v[100:103]
	v_mfma_f32_16x16x32_bf16 v[88:91], v[148:151], v[210:213], v[88:91]
	v_mfma_f32_16x16x32_bf16 v[84:87], v[156:159], v[210:213], v[84:87]
	v_mfma_f32_16x16x32_bf16 v[72:75], v[148:151], v[218:221], v[72:75]
	v_mfma_f32_16x16x32_bf16 v[68:71], v[156:159], v[218:221], v[68:71]
	v_mfma_f32_16x16x32_bf16 v[120:123], v[152:155], v[198:201], v[120:123]
	v_mfma_f32_16x16x32_bf16 v[116:119], v[160:163], v[198:201], v[116:119]
	v_mfma_f32_16x16x32_bf16 v[104:107], v[152:155], v[206:209], v[104:107]
	v_mfma_f32_16x16x32_bf16 v[100:103], v[160:163], v[206:209], v[100:103]
	v_mfma_f32_16x16x32_bf16 v[88:91], v[152:155], v[214:217], v[88:91]
	v_mfma_f32_16x16x32_bf16 v[84:87], v[160:163], v[214:217], v[84:87]
	v_mfma_f32_16x16x32_bf16 v[72:75], v[152:155], v[236:239], v[72:75]
	v_mfma_f32_16x16x32_bf16 v[68:71], v[160:163], v[236:239], v[68:71]
	s_setprio 0
	s_barrier
	s_add_i32 s61, s61, s73
	v_lshl_add_u64 v[168:169], s[50:51], 0, v[182:183]
	s_mov_b32 m0, s61
	ds_read_b128 v[164:167], v235 offset:16384
	ds_read_b128 v[198:201], v235 offset:17408
	ds_read_b128 v[202:205], v235 offset:18432
	ds_read_b128 v[206:209], v235 offset:19456
	ds_read_b128 v[210:213], v235 offset:20480
	ds_read_b128 v[214:217], v235 offset:21504
	ds_read_b128 v[218:221], v235 offset:22528
	ds_read_b128 v[236:239], v235 offset:23552
	global_load_lds_dwordx4 v[168:169], off
	s_add_i32 m0, s61, 0x2000
	s_add_u32 s78, s50, 0x80000
	v_lshl_add_u64 v[222:223], s[50:51], 0, v[186:187]
	s_addc_u32 s79, s51, 0
	s_add_i32 s61, s63, s73
	global_load_lds_dwordx4 v[222:223], off
	v_lshl_add_u64 v[2:3], s[78:79], 0, v[182:183]
	s_mov_b32 m0, s61
	v_lshl_add_u64 v[244:245], s[76:77], 0, v[180:181]
	global_load_lds_dwordx4 v[2:3], off
	v_lshl_add_u64 v[2:3], s[78:79], 0, v[186:187]
	s_add_i32 m0, s61, 0x2000
	v_lshl_add_u64 v[246:247], s[76:77], 0, v[184:185]
	global_load_lds_dwordx4 v[2:3], off
	s_mov_b32 m0, s82
	s_nop 0
	global_load_lds_dwordx4 v[244:245], off
	s_mov_b32 m0, s83
	s_nop 0
	global_load_lds_dwordx4 v[246:247], off
	s_waitcnt vmcnt(8)
	s_waitcnt lgkmcnt(0)
	s_barrier
; #define PG8_STAGE(bufoff, gbase, voff) do { _Pragma("unroll") for (int _i = 0; _i < 2; ++_i) \
;         __builtin_amdgcn_global_load_lds((const unsigned*)((const char*)(gbase) + (voff)[_i]), (PG8_LAS unsigned*)(lds + (bufoff) + ldsw + _i * 8192), 16, 0, 0); } while (0)
; #define PG8_LDA(dst, b, h) do { _Pragma("unroll") for (int m = 0; m < 4; ++m) _Pragma("unroll") for (int k = 0; k < 2; ++k) dst[m][k] = *(const PG8_LAS bf16x8*)(lds + PG8_SA(b, h) + aoff + m * 2048 + k * 1024); } while (0)
; #define PG8_LDB(dst, b, h) do { _Pragma("unroll") for (int n = 0; n < 2; ++n) _Pragma("unroll") for (int k = 0; k < 2; ++k) dst[n][k] = *(const PG8_LAS bf16x8*)(lds + PG8_SB(b, h) + boff + n * 2048 + k * 1024); } while (0)
; #define PG8_MMA(ai, bj, At, Bt) do { __builtin_amdgcn_s_setprio(1); _Pragma("unroll") for (int m = 0; m < 4; ++m) _Pragma("unroll") for (int n = 0; n < 2; ++n) _Pragma("unroll") for (int k = 0; k < 2; ++k) \
;         acc[ai][bj][m][n] = __builtin_amdgcn_mfma_f32_16x16x32_bf16(Bt[n][k], At[m][k], acc[ai][bj][m][n], 0, 0, 0); __builtin_amdgcn_s_setprio(0); } while (0)
; #define PG8_WAIT_V(n) asm volatile("s_waitcnt vmcnt(" #n ")" ::: "memory")
; #define PG8_WAIT_L(n) asm volatile("s_waitcnt lgkmcnt(" #n ")" ::: "memory")
; #define PG8_BAR __builtin_amdgcn_s_barrier()
; #define PG8_SCHED __builtin_amdgcn_sched_barrier(0)
; template <class Epi, class Sched, bool ALIGN_EPI = false, bool SP2 = false>
; __device__ __forceinline__ void gemm_phase(PG8_LAS unsigned char* lds, const Gemm g, const Sched& S, const Epi& E) {
;     ...
;             PG8_WAIT_V(8); PG8_WAIT_L(0); PG8_BAR; PG8_MMA(1, 0, At, B0); PG8_MMA(1, 1, At, B1); PG8_BAR; PG8_SCHED;
;             PG8_LDB(B0, 1, 0); PG8_LDB(B1, 1, 1); PG8_SCHED; PG8_LDA(At, 1, 0); PG8_STAGE(PG8_SA(0, 1), a2 + hstep, voffA);
;             PG8_WAIT_V(8); PG8_WAIT_L(0); PG8_BAR; PG8_MMA(0, 0, At, B0); PG8_MMA(0, 1, At, B1); PG8_BAR; PG8_SCHED;
;             PG8_LDA(At, 1, 1); PG8_STAGE(PG8_SB(1, 0), b3, voffB); PG8_STAGE(PG8_SB(1, 1), b3 + hstep, voffB); PG8_STAGE(PG8_SA(1, 0), a3, voffA);
	s_setprio 1
	s_waitcnt lgkmcnt(0)
	v_mfma_f32_16x16x32_bf16 v[64:67], v[124:127], v[164:167], v[64:67]
	v_mfma_f32_16x16x32_bf16 v[60:63], v[132:135], v[164:167], v[60:63]
	v_mfma_f32_16x16x32_bf16 v[48:51], v[124:127], v[202:205], v[48:51]
	v_mfma_f32_16x16x32_bf16 v[44:47], v[132:135], v[202:205], v[44:47]
	v_mfma_f32_16x16x32_bf16 v[32:35], v[124:127], v[210:213], v[32:35]
	v_mfma_f32_16x16x32_bf16 v[28:31], v[132:135], v[210:213], v[28:31]
	v_mfma_f32_16x16x32_bf16 v[16:19], v[124:127], v[218:221], v[16:19]
	v_mfma_f32_16x16x32_bf16 v[12:15], v[132:135], v[218:221], v[12:15]
	v_mfma_f32_16x16x32_bf16 v[64:67], v[128:131], v[198:201], v[64:67]
	v_mfma_f32_16x16x32_bf16 v[60:63], v[140:143], v[198:201], v[60:63]
	v_mfma_f32_16x16x32_bf16 v[48:51], v[128:131], v[206:209], v[48:51]
	v_mfma_f32_16x16x32_bf16 v[44:47], v[140:143], v[206:209], v[44:47]
	v_mfma_f32_16x16x32_bf16 v[32:35], v[128:131], v[214:217], v[32:35]
	v_mfma_f32_16x16x32_bf16 v[28:31], v[140:143], v[214:217], v[28:31]
	v_mfma_f32_16x16x32_bf16 v[16:19], v[128:131], v[236:239], v[16:19]
	v_mfma_f32_16x16x32_bf16 v[12:15], v[140:143], v[236:239], v[12:15]
	v_mfma_f32_16x16x32_bf16 v[56:59], v[148:151], v[164:167], v[56:59]
	v_mfma_f32_16x16x32_bf16 v[52:55], v[156:159], v[164:167], v[52:55]
	v_mfma_f32_16x16x32_bf16 v[40:43], v[148:151], v[202:205], v[40:43]
	v_mfma_f32_16x16x32_bf16 v[36:39], v[156:159], v[202:205], v[36:39]
	v_mfma_f32_16x16x32_bf16 v[24:27], v[148:151], v[210:213], v[24:27]
	v_mfma_f32_16x16x32_bf16 v[20:23], v[156:159], v[210:213], v[20:23]
	v_mfma_f32_16x16x32_bf16 v[8:11], v[148:151], v[218:221], v[8:11]
	v_mfma_f32_16x16x32_bf16 v[2:5], v[156:159], v[218:221], v[4:7]
	v_mfma_f32_16x16x32_bf16 v[56:59], v[152:155], v[198:201], v[56:59]
	v_mfma_f32_16x16x32_bf16 v[52:55], v[160:163], v[198:201], v[52:55]
	v_mfma_f32_16x16x32_bf16 v[40:43], v[152:155], v[206:209], v[40:43]
	v_mfma_f32_16x16x32_bf16 v[36:39], v[160:163], v[206:209], v[36:39]
	v_mfma_f32_16x16x32_bf16 v[24:27], v[152:155], v[214:217], v[24:27]
	v_mfma_f32_16x16x32_bf16 v[20:23], v[160:163], v[214:217], v[20:23]
	v_mfma_f32_16x16x32_bf16 v[8:11], v[152:155], v[236:239], v[8:11]
	v_mfma_f32_16x16x32_bf16 v[2:5], v[160:163], v[236:239], v[2:5]
	s_setprio 0
	s_barrier
	s_add_i32 s61, 0, 0x18000
	v_add_u32_e32 v0, s61, v234
	s_add_i32 s63, 0, 0x1c000
	ds_read_b128 v[124:127], v0
	ds_read_b128 v[128:131], v0 offset:1024
	ds_read_b128 v[132:135], v0 offset:2048
	ds_read_b128 v[140:143], v0 offset:3072
	v_add_u32_e32 v0, s63, v234
	ds_read_b128 v[148:151], v0
	ds_read_b128 v[152:155], v0 offset:1024
	ds_read_b128 v[156:159], v0 offset:2048
	ds_read_b128 v[160:163], v0 offset:3072
	s_add_u32 s76, s76, 0x80000
	s_addc_u32 s77, s77, 0
	s_mov_b32 m0, s84
	v_lshl_add_u64 v[6:7], s[76:77], 0, v[180:181]
	ds_read_b128 v[164:167], v235 offset:32768
	ds_read_b128 v[198:201], v235 offset:33792
	ds_read_b128 v[202:205], v235 offset:34816
	ds_read_b128 v[206:209], v235 offset:35840
	ds_read_b128 v[210:213], v235 offset:36864
	ds_read_b128 v[214:217], v235 offset:37888
	ds_read_b128 v[218:221], v235 offset:38912
	ds_read_b128 v[236:239], v235 offset:39936
	global_load_lds_dwordx4 v[6:7], off
	v_lshl_add_u64 v[6:7], s[76:77], 0, v[184:185]
	s_mov_b32 m0, s85
	s_nop 0
	global_load_lds_dwordx4 v[6:7], off
	s_waitcnt vmcnt(8)
	s_waitcnt lgkmcnt(0)
	s_barrier
	s_setprio 1
	s_waitcnt lgkmcnt(0)
	v_mfma_f32_16x16x32_bf16 v[144:147], v[124:127], v[164:167], v[144:147]
	v_mfma_f32_16x16x32_bf16 v[136:139], v[132:135], v[164:167], v[136:139]
	v_mfma_f32_16x16x32_bf16 v[112:115], v[124:127], v[202:205], v[112:115]
	v_mfma_f32_16x16x32_bf16 v[108:111], v[132:135], v[202:205], v[108:111]
	v_mfma_f32_16x16x32_bf16 v[96:99], v[124:127], v[210:213], v[96:99]
	v_mfma_f32_16x16x32_bf16 v[92:95], v[132:135], v[210:213], v[92:95]
	v_mfma_f32_16x16x32_bf16 v[80:83], v[124:127], v[218:221], v[80:83]
	v_mfma_f32_16x16x32_bf16 v[76:79], v[132:135], v[218:221], v[76:79]
	v_mfma_f32_16x16x32_bf16 v[144:147], v[128:131], v[198:201], v[144:147]
	v_mfma_f32_16x16x32_bf16 v[136:139], v[140:143], v[198:201], v[136:139]
	v_mfma_f32_16x16x32_bf16 v[112:115], v[128:131], v[206:209], v[112:115]
	v_mfma_f32_16x16x32_bf16 v[108:111], v[140:143], v[206:209], v[108:111]
	v_mfma_f32_16x16x32_bf16 v[96:99], v[128:131], v[214:217], v[96:99]
	v_mfma_f32_16x16x32_bf16 v[92:95], v[140:143], v[214:217], v[92:95]
	v_mfma_f32_16x16x32_bf16 v[80:83], v[128:131], v[236:239], v[80:83]
	v_mfma_f32_16x16x32_bf16 v[76:79], v[140:143], v[236:239], v[76:79]
	v_mfma_f32_16x16x32_bf16 v[120:123], v[148:151], v[164:167], v[120:123]
	v_mfma_f32_16x16x32_bf16 v[116:119], v[156:159], v[164:167], v[116:119]
	v_mfma_f32_16x16x32_bf16 v[104:107], v[148:151], v[202:205], v[104:107]
	v_mfma_f32_16x16x32_bf16 v[100:103], v[156:159], v[202:205], v[100:103]
	v_mfma_f32_16x16x32_bf16 v[88:91], v[148:151], v[210:213], v[88:91]
	v_mfma_f32_16x16x32_bf16 v[84:87], v[156:159], v[210:213], v[84:87]
	v_mfma_f32_16x16x32_bf16 v[72:75], v[148:151], v[218:221], v[72:75]
	v_mfma_f32_16x16x32_bf16 v[68:71], v[156:159], v[218:221], v[68:71]
	v_mfma_f32_16x16x32_bf16 v[120:123], v[152:155], v[198:201], v[120:123]
	v_mfma_f32_16x16x32_bf16 v[116:119], v[160:163], v[198:201], v[116:119]
	v_mfma_f32_16x16x32_bf16 v[104:107], v[152:155], v[206:209], v[104:107]
	v_mfma_f32_16x16x32_bf16 v[100:103], v[160:163], v[206:209], v[100:103]
	v_mfma_f32_16x16x32_bf16 v[88:91], v[152:155], v[214:217], v[88:91]
	v_mfma_f32_16x16x32_bf16 v[84:87], v[160:163], v[214:217], v[84:87]
	v_mfma_f32_16x16x32_bf16 v[72:75], v[152:155], v[236:239], v[72:75]
	v_mfma_f32_16x16x32_bf16 v[68:71], v[160:163], v[236:239], v[68:71]
	s_setprio 0
	s_barrier
; #define PG8_STAGE(bufoff, gbase, voff) do { _Pragma("unroll") for (int _i = 0; _i < 2; ++_i) \
;         __builtin_amdgcn_global_load_lds((const unsigned*)((const char*)(gbase) + (voff)[_i]), (PG8_LAS unsigned*)(lds + (bufoff) + ldsw + _i * 8192), 16, 0, 0); } while (0)
; #define PG8_LDA(dst, b, h) do { _Pragma("unroll") for (int m = 0; m < 4; ++m) _Pragma("unroll") for (int k = 0; k < 2; ++k) dst[m][k] = *(const PG8_LAS bf16x8*)(lds + PG8_SA(b, h) + aoff + m * 2048 + k * 1024); } while (0)
; #define PG8_MMA(ai, bj, At, Bt) do { __builtin_amdgcn_s_setprio(1); _Pragma("unroll") for (int m = 0; m < 4; ++m) _Pragma("unroll") for (int n = 0; n < 2; ++n) _Pragma("unroll") for (int k = 0; k < 2; ++k) \
;         acc[ai][bj][m][n] = __builtin_amdgcn_mfma_f32_16x16x32_bf16(Bt[n][k], At[m][k], acc[ai][bj][m][n], 0, 0, 0); __builtin_amdgcn_s_setprio(0); } while (0)
; #define PG8_WAIT_V(n) asm volatile("s_waitcnt vmcnt(" #n ")" ::: "memory")
; #define PG8_WAIT_L(n) asm volatile("s_waitcnt lgkmcnt(" #n ")" ::: "memory")
; #define PG8_BAR __builtin_amdgcn_s_barrier()
; #define PG8_SCHED __builtin_amdgcn_sched_barrier(0)
; template <class Epi, class Sched, bool ALIGN_EPI = false, bool SP2 = false>
; __device__ __forceinline__ void gemm_phase(PG8_LAS unsigned char* lds, const Gemm g, const Sched& S, const Epi& E) {
;     ...
;             PG8_LDA(At, 1, 1); PG8_STAGE(PG8_SB(1, 0), b3, voffB); PG8_STAGE(PG8_SB(1, 1), b3 + hstep, voffB); PG8_STAGE(PG8_SA(1, 0), a3, voffA);
;             PG8_WAIT_V(8); PG8_WAIT_L(0); PG8_BAR; PG8_MMA(1, 0, At, B0); PG8_MMA(1, 1, At, B1); PG8_BAR; PG8_SCHED;
	s_add_i32 s61, s61, s73
	v_lshl_add_u64 v[6:7], v[168:169], 0, s[12:13]
	s_mov_b32 m0, s61
	ds_read_b128 v[164:167], v235 offset:49152
	ds_read_b128 v[198:201], v235 offset:50176
	ds_read_b128 v[202:205], v235 offset:51200
	ds_read_b128 v[206:209], v235 offset:52224
	ds_read_b128 v[210:213], v235 offset:53248
	ds_read_b128 v[214:217], v235 offset:54272
	ds_read_b128 v[218:221], v235 offset:55296
	ds_read_b128 v[236:239], v235 offset:56320
	global_load_lds_dwordx4 v[6:7], off
	s_add_i32 m0, s61, 0x2000
	s_add_u32 s50, s50, 0x80080
	v_lshl_add_u64 v[6:7], v[222:223], 0, s[12:13]
	s_addc_u32 s51, s51, 0
	s_add_i32 s61, s63, s73
	global_load_lds_dwordx4 v[6:7], off
	v_lshl_add_u64 v[6:7], s[50:51], 0, v[182:183]
	s_mov_b32 m0, s61
	s_nop 0
	global_load_lds_dwordx4 v[6:7], off
	v_lshl_add_u64 v[6:7], s[50:51], 0, v[186:187]
	s_add_i32 m0, s61, 0x2000
	s_nop 0
	global_load_lds_dwordx4 v[6:7], off
	v_lshl_add_u64 v[6:7], v[244:245], 0, s[12:13]
	s_mov_b32 m0, s87
	s_nop 0
	global_load_lds_dwordx4 v[6:7], off
	v_lshl_add_u64 v[6:7], v[246:247], 0, s[12:13]
	s_mov_b32 m0, s88
	s_nop 0
	global_load_lds_dwordx4 v[6:7], off
	s_waitcnt vmcnt(8)
	s_waitcnt lgkmcnt(0)
	s_barrier
	s_setprio 1
	s_waitcnt lgkmcnt(0)
	v_mfma_f32_16x16x32_bf16 v[64:67], v[124:127], v[164:167], v[64:67]
	v_mfma_f32_16x16x32_bf16 v[60:63], v[132:135], v[164:167], v[60:63]
	v_mfma_f32_16x16x32_bf16 v[48:51], v[124:127], v[202:205], v[48:51]
	v_mfma_f32_16x16x32_bf16 v[44:47], v[132:135], v[202:205], v[44:47]
	v_mfma_f32_16x16x32_bf16 v[32:35], v[124:127], v[210:213], v[32:35]
	v_mfma_f32_16x16x32_bf16 v[28:31], v[132:135], v[210:213], v[28:31]
	v_mfma_f32_16x16x32_bf16 v[16:19], v[124:127], v[218:221], v[16:19]
	v_mfma_f32_16x16x32_bf16 v[12:15], v[132:135], v[218:221], v[12:15]
	v_mfma_f32_16x16x32_bf16 v[64:67], v[128:131], v[198:201], v[64:67]
	v_mfma_f32_16x16x32_bf16 v[60:63], v[140:143], v[198:201], v[60:63]
	v_mfma_f32_16x16x32_bf16 v[48:51], v[128:131], v[206:209], v[48:51]
	v_mfma_f32_16x16x32_bf16 v[44:47], v[140:143], v[206:209], v[44:47]
	v_mfma_f32_16x16x32_bf16 v[32:35], v[128:131], v[214:217], v[32:35]
	v_mfma_f32_16x16x32_bf16 v[28:31], v[140:143], v[214:217], v[28:31]
	v_mfma_f32_16x16x32_bf16 v[16:19], v[128:131], v[236:239], v[16:19]
	v_mfma_f32_16x16x32_bf16 v[12:15], v[140:143], v[236:239], v[12:15]
	v_mfma_f32_16x16x32_bf16 v[56:59], v[148:151], v[164:167], v[56:59]
	v_mfma_f32_16x16x32_bf16 v[52:55], v[156:159], v[164:167], v[52:55]
	v_mfma_f32_16x16x32_bf16 v[40:43], v[148:151], v[202:205], v[40:43]
	v_mfma_f32_16x16x32_bf16 v[36:39], v[156:159], v[202:205], v[36:39]
	v_mfma_f32_16x16x32_bf16 v[24:27], v[148:151], v[210:213], v[24:27]
	v_mfma_f32_16x16x32_bf16 v[20:23], v[156:159], v[210:213], v[20:23]
	v_mfma_f32_16x16x32_bf16 v[6:9], v[148:151], v[218:221], v[8:11]
	v_mfma_f32_16x16x32_bf16 v[2:5], v[156:159], v[218:221], v[2:5]
	v_mfma_f32_16x16x32_bf16 v[56:59], v[152:155], v[198:201], v[56:59]
	v_mfma_f32_16x16x32_bf16 v[52:55], v[160:163], v[198:201], v[52:55]
	v_mfma_f32_16x16x32_bf16 v[40:43], v[152:155], v[206:209], v[40:43]
	v_mfma_f32_16x16x32_bf16 v[36:39], v[160:163], v[206:209], v[36:39]
	v_mfma_f32_16x16x32_bf16 v[24:27], v[152:155], v[214:217], v[24:27]
	v_mfma_f32_16x16x32_bf16 v[20:23], v[160:163], v[214:217], v[20:23]
	v_mfma_f32_16x16x32_bf16 v[8:11], v[152:155], v[236:239], v[6:9]
	v_mfma_f32_16x16x32_bf16 v[4:7], v[160:163], v[236:239], v[2:5]
	s_setprio 0
	s_barrier
	s_add_i32 s58, s58, 2
	s_add_u32 s48, s48, 0x100
	s_addc_u32 s49, s49, 0
	s_add_u32 s39, s39, 0x100
	s_addc_u32 s47, s47, 0
	s_cmp_gt_u32 s58, 29
	s_cbranch_scc0 .LBB0_117
	s_and_b64 vcc, exec, s[30:31]
	s_cbranch_vccz .LBB0_120
	s_barrier

; #define PG8_STAGE(bufoff, gbase, voff) do { _Pragma("unroll") for (int _i = 0; _i < 2; ++_i) \
;         __builtin_amdgcn_global_load_lds((const unsigned*)((const char*)(gbase) + (voff)[_i]), (PG8_LAS unsigned*)(lds + (bufoff) + ldsw + _i * 8192), 16, 0, 0); } while (0)
; #define PG8_LDA(dst, b, h) do { _Pragma("unroll") for (int m = 0; m < 4; ++m) _Pragma("unroll") for (int k = 0; k < 2; ++k) dst[m][k] = *(const PG8_LAS bf16x8*)(lds + PG8_SA(b, h) + aoff + m * 2048 + k * 1024); } while (0)
; #define PG8_LDB(dst, b, h) do { _Pragma("unroll") for (int n = 0; n < 2; ++n) _Pragma("unroll") for (int k = 0; k < 2; ++k) dst[n][k] = *(const PG8_LAS bf16x8*)(lds + PG8_SB(b, h) + boff + n * 2048 + k * 1024); } while (0)
; #define PG8_MMA(ai, bj, At, Bt) do { __builtin_amdgcn_s_setprio(1); _Pragma("unroll") for (int m = 0; m < 4; ++m) _Pragma("unroll") for (int n = 0; n < 2; ++n) _Pragma("unroll") for (int k = 0; k < 2; ++k) \
;         acc[ai][bj][m][n] = __builtin_amdgcn_mfma_f32_16x16x32_bf16(Bt[n][k], At[m][k], acc[ai][bj][m][n], 0, 0, 0); __builtin_amdgcn_s_setprio(0); } while (0)
; #define PG8_WAIT_V(n) asm volatile("s_waitcnt vmcnt(" #n ")" ::: "memory")
; #define PG8_WAIT_L(n) asm volatile("s_waitcnt lgkmcnt(" #n ")" ::: "memory")
; template <class Epi, class Sched, bool ALIGN_EPI = false, bool SP2 = false>
; __device__ __forceinline__ void gemm_phase(PG8_LAS unsigned char* lds, const Gemm g, const Sched& S, const Epi& E) {
;     ...
;             const bool last = (t == nt - 2);
;             const char* a1 = cA + (size_t)(t + 1) * kstep;
;             const char* a2 = last ? nA : cA + (size_t)(t + 2) * kstep; const char* b2 = last ? nB : cB + (size_t)(t + 2) * kstep;
;             const char* a3 = a2 + kstep; const char* b3 = b2 + kstep;
;             if (last && has_next) S.a_ready(nxt);
;             if constexpr (SP2) {
;             PG8_LDB(B0, 0, 0); PG8_LDB(B1, 0, 1); PG8_SCHED; PG8_LDA(At, 0, 0); PG8_STAGE(PG8_SA(1, 1), a1 + hstep, voffA);
;             PG8_WAIT_V(8); PG8_WAIT_L(0); PG8_BAR; PG8_MMA(0, 0, At, B0); PG8_MMA(0, 1, At, B1); PG8_BAR; PG8_SCHED;
;             PG8_LDA(At, 0, 1); PG8_STAGE(PG8_SB(0, 0), b2, voffB); PG8_STAGE(PG8_SB(0, 1), b2 + hstep, voffB); PG8_STAGE(PG8_SA(0, 0), a2, voffA);
;             PG8_WAIT_V(8); PG8_WAIT_L(0); PG8_BAR; PG8_MMA(1, 0, At, B0); PG8_MMA(1, 1, At, B1); PG8_BAR; PG8_SCHED;
.LBB0_1427:
	s_add_i32 s96, s74, 2
	s_add_u32 s97, s44, 0x80
	s_addc_u32 s75, s45, 0
	s_add_i32 s27, 0, 0x10000
	s_cmp_eq_u32 s91, s74
	s_cselect_b32 s75, s24, s75
	s_cselect_b32 s74, s25, s97
	s_cselect_b32 vcc_hi, s53, s95
	s_cselect_b32 vcc_lo, s61, s94
	s_add_i32 s97, 0, 0x14000
	v_add_u32_e32 v142, s27, v185
	v_add_u32_e32 v168, s97, v185
	ds_read_b128 v[130:133], v142
	ds_read_b128 v[134:137], v142 offset:1024
	ds_read_b128 v[138:141], v142 offset:2048
	ds_read_b128 v[142:145], v142 offset:3072
	ds_read_b128 v[146:149], v168
	ds_read_b128 v[150:153], v168 offset:1024
	ds_read_b128 v[164:167], v168 offset:2048
	ds_read_b128 v[180:183], v168 offset:3072
	v_lshl_add_u64 v[168:169], s[44:45], 0, v[160:161]
	s_add_i32 m0, s83, 0xc000
	ds_read_b128 v[190:193], v187
	ds_read_b128 v[194:197], v187 offset:1024
	ds_read_b128 v[198:201], v187 offset:2048
	ds_read_b128 v[202:205], v187 offset:3072
	ds_read_b128 v[206:209], v187 offset:4096
	ds_read_b128 v[210:213], v187 offset:5120
	ds_read_b128 v[214:217], v187 offset:6144
	ds_read_b128 v[218:221], v187 offset:7168
	global_load_lds_dwordx4 v[168:169], off
	v_lshl_add_u64 v[168:169], s[44:45], 0, v[162:163]
	s_add_i32 m0, s83, 0xe000
	s_nop 0
	global_load_lds_dwordx4 v[168:169], off
	s_waitcnt vmcnt(8)
	s_waitcnt lgkmcnt(0)
	s_barrier
	s_setprio 1
	s_waitcnt lgkmcnt(0)
	v_mfma_f32_16x16x32_bf16 v[126:129], v[130:133], v[190:193], v[126:129]
	v_mfma_f32_16x16x32_bf16 v[122:125], v[138:141], v[190:193], v[122:125]
	v_mfma_f32_16x16x32_bf16 v[110:113], v[130:133], v[198:201], v[110:113]
	v_mfma_f32_16x16x32_bf16 v[106:109], v[138:141], v[198:201], v[106:109]
	v_mfma_f32_16x16x32_bf16 v[94:97], v[130:133], v[206:209], v[94:97]
	v_mfma_f32_16x16x32_bf16 v[90:93], v[138:141], v[206:209], v[90:93]
	v_mfma_f32_16x16x32_bf16 v[78:81], v[130:133], v[214:217], v[78:81]
	v_mfma_f32_16x16x32_bf16 v[74:77], v[138:141], v[214:217], v[74:77]
	v_mfma_f32_16x16x32_bf16 v[126:129], v[134:137], v[194:197], v[126:129]
	v_mfma_f32_16x16x32_bf16 v[122:125], v[142:145], v[194:197], v[122:125]
	v_mfma_f32_16x16x32_bf16 v[110:113], v[134:137], v[202:205], v[110:113]
	v_mfma_f32_16x16x32_bf16 v[106:109], v[142:145], v[202:205], v[106:109]
	v_mfma_f32_16x16x32_bf16 v[94:97], v[134:137], v[210:213], v[94:97]
	v_mfma_f32_16x16x32_bf16 v[90:93], v[142:145], v[210:213], v[90:93]
	v_mfma_f32_16x16x32_bf16 v[78:81], v[134:137], v[218:221], v[78:81]
	v_mfma_f32_16x16x32_bf16 v[74:77], v[142:145], v[218:221], v[74:77]
	v_mfma_f32_16x16x32_bf16 v[118:121], v[146:149], v[190:193], v[118:121]
	v_mfma_f32_16x16x32_bf16 v[114:117], v[164:167], v[190:193], v[114:117]
	v_mfma_f32_16x16x32_bf16 v[102:105], v[146:149], v[198:201], v[102:105]
	v_mfma_f32_16x16x32_bf16 v[98:101], v[164:167], v[198:201], v[98:101]
	v_mfma_f32_16x16x32_bf16 v[86:89], v[146:149], v[206:209], v[86:89]
	v_mfma_f32_16x16x32_bf16 v[82:85], v[164:167], v[206:209], v[82:85]
	v_mfma_f32_16x16x32_bf16 v[70:73], v[146:149], v[214:217], v[70:73]
	v_mfma_f32_16x16x32_bf16 v[66:69], v[164:167], v[214:217], v[66:69]
	v_mfma_f32_16x16x32_bf16 v[118:121], v[150:153], v[194:197], v[118:121]
	v_mfma_f32_16x16x32_bf16 v[114:117], v[180:183], v[194:197], v[114:117]
	v_mfma_f32_16x16x32_bf16 v[102:105], v[150:153], v[202:205], v[102:105]
	v_mfma_f32_16x16x32_bf16 v[98:101], v[180:183], v[202:205], v[98:101]
	v_mfma_f32_16x16x32_bf16 v[86:89], v[150:153], v[210:213], v[86:89]
	v_mfma_f32_16x16x32_bf16 v[82:85], v[180:183], v[210:213], v[82:85]
	v_mfma_f32_16x16x32_bf16 v[70:73], v[150:153], v[218:221], v[70:73]
	v_mfma_f32_16x16x32_bf16 v[66:69], v[180:183], v[218:221], v[66:69]
	s_setprio 0
	s_barrier
	s_add_i32 s27, s27, s82
	v_lshl_add_u64 v[168:169], vcc, 0, v[0:1]
	s_mov_b32 m0, s27
	ds_read_b128 v[190:193], v187 offset:16384
	ds_read_b128 v[194:197], v187 offset:17408
	ds_read_b128 v[198:201], v187 offset:18432
	ds_read_b128 v[202:205], v187 offset:19456
	ds_read_b128 v[206:209], v187 offset:20480
	ds_read_b128 v[210:213], v187 offset:21504
	ds_read_b128 v[214:217], v187 offset:22528
	ds_read_b128 v[218:221], v187 offset:23552
	global_load_lds_dwordx4 v[168:169], off
	s_add_i32 m0, s27, 0x2000
	v_lshl_add_u64 v[222:223], vcc, 0, v[154:155]
	s_add_u32 vcc_lo, vcc_lo, s70
	s_addc_u32 vcc_hi, vcc_hi, 0
	s_add_i32 s27, s97, s82
	global_load_lds_dwordx4 v[222:223], off
	v_lshl_add_u64 v[232:233], vcc, 0, v[0:1]
	s_mov_b32 m0, s27
	v_lshl_add_u64 v[234:235], vcc, 0, v[154:155]
	global_load_lds_dwordx4 v[232:233], off
	s_add_i32 m0, s27, 0x2000
	v_lshl_add_u64 v[236:237], s[74:75], 0, v[158:159]
	global_load_lds_dwordx4 v[234:235], off
	s_mov_b32 m0, s83
	v_lshl_add_u64 v[238:239], s[74:75], 0, v[156:157]
	global_load_lds_dwordx4 v[236:237], off
	s_mov_b32 m0, s84
	s_nop 0
	global_load_lds_dwordx4 v[238:239], off
	s_waitcnt vmcnt(8)
	s_waitcnt lgkmcnt(0)
	s_barrier
; #define PG8_STAGE(bufoff, gbase, voff) do { _Pragma("unroll") for (int _i = 0; _i < 2; ++_i) \
;         __builtin_amdgcn_global_load_lds((const unsigned*)((const char*)(gbase) + (voff)[_i]), (PG8_LAS unsigned*)(lds + (bufoff) + ldsw + _i * 8192), 16, 0, 0); } while (0)
; #define PG8_LDA(dst, b, h) do { _Pragma("unroll") for (int m = 0; m < 4; ++m) _Pragma("unroll") for (int k = 0; k < 2; ++k) dst[m][k] = *(const PG8_LAS bf16x8*)(lds + PG8_SA(b, h) + aoff + m * 2048 + k * 1024); } while (0)
; #define PG8_LDB(dst, b, h) do { _Pragma("unroll") for (int n = 0; n < 2; ++n) _Pragma("unroll") for (int k = 0; k < 2; ++k) dst[n][k] = *(const PG8_LAS bf16x8*)(lds + PG8_SB(b, h) + boff + n * 2048 + k * 1024); } while (0)
; #define PG8_MMA(ai, bj, At, Bt) do { __builtin_amdgcn_s_setprio(1); _Pragma("unroll") for (int m = 0; m < 4; ++m) _Pragma("unroll") for (int n = 0; n < 2; ++n) _Pragma("unroll") for (int k = 0; k < 2; ++k) \
;         acc[ai][bj][m][n] = __builtin_amdgcn_mfma_f32_16x16x32_bf16(Bt[n][k], At[m][k], acc[ai][bj][m][n], 0, 0, 0); __builtin_amdgcn_s_setprio(0); } while (0)
; #define PG8_WAIT_V(n) asm volatile("s_waitcnt vmcnt(" #n ")" ::: "memory")
; #define PG8_WAIT_L(n) asm volatile("s_waitcnt lgkmcnt(" #n ")" ::: "memory")
; #define PG8_BAR __builtin_amdgcn_s_barrier()
; #define PG8_SCHED __builtin_amdgcn_sched_barrier(0)
; template <class Epi, class Sched, bool ALIGN_EPI = false, bool SP2 = false>
; __device__ __forceinline__ void gemm_phase(PG8_LAS unsigned char* lds, const Gemm g, const Sched& S, const Epi& E) {
;     ...
;             PG8_WAIT_V(8); PG8_WAIT_L(0); PG8_BAR; PG8_MMA(1, 0, At, B0); PG8_MMA(1, 1, At, B1); PG8_BAR; PG8_SCHED;
;             PG8_LDB(B0, 1, 0); PG8_LDB(B1, 1, 1); PG8_SCHED; PG8_LDA(At, 1, 0); PG8_STAGE(PG8_SA(0, 1), a2 + hstep, voffA);
;             PG8_WAIT_V(8); PG8_WAIT_L(0); PG8_BAR; PG8_MMA(0, 0, At, B0); PG8_MMA(0, 1, At, B1); PG8_BAR; PG8_SCHED;
;             PG8_LDA(At, 1, 1); PG8_STAGE(PG8_SB(1, 0), b3, voffB); PG8_STAGE(PG8_SB(1, 1), b3 + hstep, voffB); PG8_STAGE(PG8_SA(1, 0), a3, voffA);
	s_setprio 1
	s_waitcnt lgkmcnt(0)
	v_mfma_f32_16x16x32_bf16 v[62:65], v[130:133], v[190:193], v[62:65]
	v_mfma_f32_16x16x32_bf16 v[58:61], v[138:141], v[190:193], v[58:61]
	v_mfma_f32_16x16x32_bf16 v[46:49], v[130:133], v[198:201], v[46:49]
	v_mfma_f32_16x16x32_bf16 v[42:45], v[138:141], v[198:201], v[42:45]
	v_mfma_f32_16x16x32_bf16 v[30:33], v[130:133], v[206:209], v[30:33]
	v_mfma_f32_16x16x32_bf16 v[26:29], v[138:141], v[206:209], v[26:29]
	v_mfma_f32_16x16x32_bf16 v[14:17], v[130:133], v[214:217], v[14:17]
	v_mfma_f32_16x16x32_bf16 v[10:13], v[138:141], v[214:217], v[10:13]
	v_mfma_f32_16x16x32_bf16 v[62:65], v[134:137], v[194:197], v[62:65]
	v_mfma_f32_16x16x32_bf16 v[58:61], v[142:145], v[194:197], v[58:61]
	v_mfma_f32_16x16x32_bf16 v[46:49], v[134:137], v[202:205], v[46:49]
	v_mfma_f32_16x16x32_bf16 v[42:45], v[142:145], v[202:205], v[42:45]
	v_mfma_f32_16x16x32_bf16 v[30:33], v[134:137], v[210:213], v[30:33]
	v_mfma_f32_16x16x32_bf16 v[26:29], v[142:145], v[210:213], v[26:29]
	v_mfma_f32_16x16x32_bf16 v[14:17], v[134:137], v[218:221], v[14:17]
	v_mfma_f32_16x16x32_bf16 v[10:13], v[142:145], v[218:221], v[10:13]
	v_mfma_f32_16x16x32_bf16 v[54:57], v[146:149], v[190:193], v[54:57]
	v_mfma_f32_16x16x32_bf16 v[50:53], v[164:167], v[190:193], v[50:53]
	v_mfma_f32_16x16x32_bf16 v[38:41], v[146:149], v[198:201], v[38:41]
	v_mfma_f32_16x16x32_bf16 v[34:37], v[164:167], v[198:201], v[34:37]
	v_mfma_f32_16x16x32_bf16 v[22:25], v[146:149], v[206:209], v[22:25]
	v_mfma_f32_16x16x32_bf16 v[18:21], v[164:167], v[206:209], v[18:21]
	v_mfma_f32_16x16x32_bf16 v[6:9], v[146:149], v[214:217], v[6:9]
	v_mfma_f32_16x16x32_bf16 v[2:5], v[164:167], v[214:217], v[2:5]
	v_mfma_f32_16x16x32_bf16 v[54:57], v[150:153], v[194:197], v[54:57]
	v_mfma_f32_16x16x32_bf16 v[50:53], v[180:183], v[194:197], v[50:53]
	v_mfma_f32_16x16x32_bf16 v[38:41], v[150:153], v[202:205], v[38:41]
	v_mfma_f32_16x16x32_bf16 v[34:37], v[180:183], v[202:205], v[34:37]
	v_mfma_f32_16x16x32_bf16 v[22:25], v[150:153], v[210:213], v[22:25]
	v_mfma_f32_16x16x32_bf16 v[18:21], v[180:183], v[210:213], v[18:21]
	v_mfma_f32_16x16x32_bf16 v[6:9], v[150:153], v[218:221], v[6:9]
	v_mfma_f32_16x16x32_bf16 v[2:5], v[180:183], v[218:221], v[2:5]
	s_setprio 0
	s_barrier
	s_add_i32 s27, 0, 0x18000
	s_add_i32 s97, 0, 0x1c000
	v_add_u32_e32 v142, s27, v185
	v_add_u32_e32 v180, s97, v185
	ds_read_b128 v[130:133], v142
	ds_read_b128 v[134:137], v142 offset:1024
	ds_read_b128 v[138:141], v142 offset:2048
	ds_read_b128 v[142:145], v142 offset:3072
	ds_read_b128 v[146:149], v180
	ds_read_b128 v[150:153], v180 offset:1024
	ds_read_b128 v[164:167], v180 offset:2048
	ds_read_b128 v[180:183], v180 offset:3072
	s_add_u32 s74, s74, s70
	s_addc_u32 s75, s75, 0
	s_mov_b32 m0, s85
	v_lshl_add_u64 v[244:245], s[74:75], 0, v[158:159]
	ds_read_b128 v[190:193], v187 offset:32768
	ds_read_b128 v[194:197], v187 offset:33792
	ds_read_b128 v[198:201], v187 offset:34816
	ds_read_b128 v[202:205], v187 offset:35840
	ds_read_b128 v[206:209], v187 offset:36864
	ds_read_b128 v[210:213], v187 offset:37888
	ds_read_b128 v[214:217], v187 offset:38912
	ds_read_b128 v[218:221], v187 offset:39936
	global_load_lds_dwordx4 v[244:245], off
	v_lshl_add_u64 v[244:245], s[74:75], 0, v[156:157]
	s_mov_b32 m0, s86
	s_nop 0
	global_load_lds_dwordx4 v[244:245], off
	s_waitcnt vmcnt(8)
	s_waitcnt lgkmcnt(0)
	s_barrier
	s_setprio 1
	s_waitcnt lgkmcnt(0)
	v_mfma_f32_16x16x32_bf16 v[126:129], v[130:133], v[190:193], v[126:129]
	v_mfma_f32_16x16x32_bf16 v[122:125], v[138:141], v[190:193], v[122:125]
	v_mfma_f32_16x16x32_bf16 v[110:113], v[130:133], v[198:201], v[110:113]
	v_mfma_f32_16x16x32_bf16 v[106:109], v[138:141], v[198:201], v[106:109]
	v_mfma_f32_16x16x32_bf16 v[94:97], v[130:133], v[206:209], v[94:97]
	v_mfma_f32_16x16x32_bf16 v[90:93], v[138:141], v[206:209], v[90:93]
	v_mfma_f32_16x16x32_bf16 v[78:81], v[130:133], v[214:217], v[78:81]
	v_mfma_f32_16x16x32_bf16 v[74:77], v[138:141], v[214:217], v[74:77]
	v_mfma_f32_16x16x32_bf16 v[126:129], v[134:137], v[194:197], v[126:129]
	v_mfma_f32_16x16x32_bf16 v[122:125], v[142:145], v[194:197], v[122:125]
	v_mfma_f32_16x16x32_bf16 v[110:113], v[134:137], v[202:205], v[110:113]
	v_mfma_f32_16x16x32_bf16 v[106:109], v[142:145], v[202:205], v[106:109]
	v_mfma_f32_16x16x32_bf16 v[94:97], v[134:137], v[210:213], v[94:97]
	v_mfma_f32_16x16x32_bf16 v[90:93], v[142:145], v[210:213], v[90:93]
	v_mfma_f32_16x16x32_bf16 v[78:81], v[134:137], v[218:221], v[78:81]
	v_mfma_f32_16x16x32_bf16 v[74:77], v[142:145], v[218:221], v[74:77]
	v_mfma_f32_16x16x32_bf16 v[118:121], v[146:149], v[190:193], v[118:121]
	v_mfma_f32_16x16x32_bf16 v[114:117], v[164:167], v[190:193], v[114:117]
	v_mfma_f32_16x16x32_bf16 v[102:105], v[146:149], v[198:201], v[102:105]
	v_mfma_f32_16x16x32_bf16 v[98:101], v[164:167], v[198:201], v[98:101]
	v_mfma_f32_16x16x32_bf16 v[86:89], v[146:149], v[206:209], v[86:89]
	v_mfma_f32_16x16x32_bf16 v[82:85], v[164:167], v[206:209], v[82:85]
	v_mfma_f32_16x16x32_bf16 v[70:73], v[146:149], v[214:217], v[70:73]
	v_mfma_f32_16x16x32_bf16 v[66:69], v[164:167], v[214:217], v[66:69]
	v_mfma_f32_16x16x32_bf16 v[118:121], v[150:153], v[194:197], v[118:121]
	v_mfma_f32_16x16x32_bf16 v[114:117], v[180:183], v[194:197], v[114:117]
	v_mfma_f32_16x16x32_bf16 v[102:105], v[150:153], v[202:205], v[102:105]
	v_mfma_f32_16x16x32_bf16 v[98:101], v[180:183], v[202:205], v[98:101]
	v_mfma_f32_16x16x32_bf16 v[86:89], v[150:153], v[210:213], v[86:89]
	v_mfma_f32_16x16x32_bf16 v[82:85], v[180:183], v[210:213], v[82:85]
	v_mfma_f32_16x16x32_bf16 v[70:73], v[150:153], v[218:221], v[70:73]
	v_mfma_f32_16x16x32_bf16 v[66:69], v[180:183], v[218:221], v[66:69]
	s_setprio 0
	s_barrier
; #define PG8_STAGE(bufoff, gbase, voff) do { _Pragma("unroll") for (int _i = 0; _i < 2; ++_i) \
;         __builtin_amdgcn_global_load_lds((const unsigned*)((const char*)(gbase) + (voff)[_i]), (PG8_LAS unsigned*)(lds + (bufoff) + ldsw + _i * 8192), 16, 0, 0); } while (0)
; #define PG8_LDA(dst, b, h) do { _Pragma("unroll") for (int m = 0; m < 4; ++m) _Pragma("unroll") for (int k = 0; k < 2; ++k) dst[m][k] = *(const PG8_LAS bf16x8*)(lds + PG8_SA(b, h) + aoff + m * 2048 + k * 1024); } while (0)
; #define PG8_MMA(ai, bj, At, Bt) do { __builtin_amdgcn_s_setprio(1); _Pragma("unroll") for (int m = 0; m < 4; ++m) _Pragma("unroll") for (int n = 0; n < 2; ++n) _Pragma("unroll") for (int k = 0; k < 2; ++k) \
;         acc[ai][bj][m][n] = __builtin_amdgcn_mfma_f32_16x16x32_bf16(Bt[n][k], At[m][k], acc[ai][bj][m][n], 0, 0, 0); __builtin_amdgcn_s_setprio(0); } while (0)
; #define PG8_WAIT_V(n) asm volatile("s_waitcnt vmcnt(" #n ")" ::: "memory")
; #define PG8_WAIT_L(n) asm volatile("s_waitcnt lgkmcnt(" #n ")" ::: "memory")
; #define PG8_BAR __builtin_amdgcn_s_barrier()
; #define PG8_SCHED __builtin_amdgcn_sched_barrier(0)
; template <class Epi, class Sched, bool ALIGN_EPI = false, bool SP2 = false>
; __device__ __forceinline__ void gemm_phase(PG8_LAS unsigned char* lds, const Gemm g, const Sched& S, const Epi& E) {
;     ...
;             PG8_LDA(At, 1, 1); PG8_STAGE(PG8_SB(1, 0), b3, voffB); PG8_STAGE(PG8_SB(1, 1), b3 + hstep, voffB); PG8_STAGE(PG8_SA(1, 0), a3, voffA);
;             PG8_WAIT_V(8); PG8_WAIT_L(0); PG8_BAR; PG8_MMA(1, 0, At, B0); PG8_MMA(1, 1, At, B1); PG8_BAR; PG8_SCHED;
	s_add_i32 s27, s27, s82
	v_lshl_add_u64 v[168:169], v[168:169], 0, s[12:13]
	s_mov_b32 m0, s27
	ds_read_b128 v[190:193], v187 offset:49152
	ds_read_b128 v[194:197], v187 offset:50176
	ds_read_b128 v[198:201], v187 offset:51200
	ds_read_b128 v[202:205], v187 offset:52224
	ds_read_b128 v[206:209], v187 offset:53248
	ds_read_b128 v[210:213], v187 offset:54272
	ds_read_b128 v[214:217], v187 offset:55296
	ds_read_b128 v[218:221], v187 offset:56320
	global_load_lds_dwordx4 v[168:169], off
	v_lshl_add_u64 v[168:169], v[222:223], 0, s[12:13]
	s_add_i32 m0, s27, 0x2000
	s_add_i32 s27, s97, s82
	global_load_lds_dwordx4 v[168:169], off
	v_lshl_add_u64 v[168:169], v[232:233], 0, s[12:13]
	s_mov_b32 m0, s27
	s_nop 0
	global_load_lds_dwordx4 v[168:169], off
	v_lshl_add_u64 v[168:169], v[234:235], 0, s[12:13]
	s_add_i32 m0, s27, 0x2000
	s_nop 0
	global_load_lds_dwordx4 v[168:169], off
	v_lshl_add_u64 v[168:169], v[236:237], 0, s[12:13]
	s_mov_b32 m0, s89
	s_nop 0
	global_load_lds_dwordx4 v[168:169], off
	v_lshl_add_u64 v[168:169], v[238:239], 0, s[12:13]
	s_mov_b32 m0, s90
	s_nop 0
	global_load_lds_dwordx4 v[168:169], off
	s_waitcnt vmcnt(8)
	s_waitcnt lgkmcnt(0)
	s_barrier
	s_setprio 1
	s_waitcnt lgkmcnt(0)
	v_mfma_f32_16x16x32_bf16 v[62:65], v[130:133], v[190:193], v[62:65]
	v_mfma_f32_16x16x32_bf16 v[58:61], v[138:141], v[190:193], v[58:61]
	v_mfma_f32_16x16x32_bf16 v[46:49], v[130:133], v[198:201], v[46:49]
	v_mfma_f32_16x16x32_bf16 v[42:45], v[138:141], v[198:201], v[42:45]
	v_mfma_f32_16x16x32_bf16 v[30:33], v[130:133], v[206:209], v[30:33]
	v_mfma_f32_16x16x32_bf16 v[26:29], v[138:141], v[206:209], v[26:29]
	v_mfma_f32_16x16x32_bf16 v[14:17], v[130:133], v[214:217], v[14:17]
	v_mfma_f32_16x16x32_bf16 v[10:13], v[138:141], v[214:217], v[10:13]
	v_mfma_f32_16x16x32_bf16 v[62:65], v[134:137], v[194:197], v[62:65]
	v_mfma_f32_16x16x32_bf16 v[58:61], v[142:145], v[194:197], v[58:61]
	v_mfma_f32_16x16x32_bf16 v[46:49], v[134:137], v[202:205], v[46:49]
	v_mfma_f32_16x16x32_bf16 v[42:45], v[142:145], v[202:205], v[42:45]
	v_mfma_f32_16x16x32_bf16 v[30:33], v[134:137], v[210:213], v[30:33]
	v_mfma_f32_16x16x32_bf16 v[26:29], v[142:145], v[210:213], v[26:29]
	v_mfma_f32_16x16x32_bf16 v[14:17], v[134:137], v[218:221], v[14:17]
	v_mfma_f32_16x16x32_bf16 v[10:13], v[142:145], v[218:221], v[10:13]
	v_mfma_f32_16x16x32_bf16 v[54:57], v[146:149], v[190:193], v[54:57]
	v_mfma_f32_16x16x32_bf16 v[50:53], v[164:167], v[190:193], v[50:53]
	v_mfma_f32_16x16x32_bf16 v[38:41], v[146:149], v[198:201], v[38:41]
	v_mfma_f32_16x16x32_bf16 v[34:37], v[164:167], v[198:201], v[34:37]
	v_mfma_f32_16x16x32_bf16 v[22:25], v[146:149], v[206:209], v[22:25]
	v_mfma_f32_16x16x32_bf16 v[18:21], v[164:167], v[206:209], v[18:21]
	v_mfma_f32_16x16x32_bf16 v[6:9], v[146:149], v[214:217], v[6:9]
	v_mfma_f32_16x16x32_bf16 v[2:5], v[164:167], v[214:217], v[2:5]
	v_mfma_f32_16x16x32_bf16 v[54:57], v[150:153], v[194:197], v[54:57]
	v_mfma_f32_16x16x32_bf16 v[50:53], v[180:183], v[194:197], v[50:53]
	v_mfma_f32_16x16x32_bf16 v[38:41], v[150:153], v[202:205], v[38:41]
	v_mfma_f32_16x16x32_bf16 v[34:37], v[180:183], v[202:205], v[34:37]
	v_mfma_f32_16x16x32_bf16 v[22:25], v[150:153], v[210:213], v[22:25]
	v_mfma_f32_16x16x32_bf16 v[18:21], v[180:183], v[210:213], v[18:21]
	v_mfma_f32_16x16x32_bf16 v[6:9], v[150:153], v[218:221], v[6:9]
	v_mfma_f32_16x16x32_bf16 v[2:5], v[180:183], v[218:221], v[2:5]
	s_setprio 0
	s_barrier
	s_add_u32 s44, s44, 0x100
	s_addc_u32 s45, s45, 0
	s_add_u32 s94, s94, 0x100
	s_addc_u32 s95, s95, 0
	s_cmp_ge_u32 s96, s88
	s_mov_b32 s74, s96
	s_cbranch_scc0 .LBB0_1427
	s_and_b64 vcc, exec, s[48:49]
	s_cbranch_vccz .LBB0_1430
	s_barrier

; #define PG8_STAGE(bufoff, gbase, voff) do { _Pragma("unroll") for (int _i = 0; _i < 2; ++_i) \
;         __builtin_amdgcn_global_load_lds((const unsigned*)((const char*)(gbase) + (voff)[_i]), (PG8_LAS unsigned*)(lds + (bufoff) + ldsw + _i * 8192), 16, 0, 0); } while (0)
; #define PG8_LDA(dst, b, h) do { _Pragma("unroll") for (int m = 0; m < 4; ++m) _Pragma("unroll") for (int k = 0; k < 2; ++k) dst[m][k] = *(const PG8_LAS bf16x8*)(lds + PG8_SA(b, h) + aoff + m * 2048 + k * 1024); } while (0)
; #define PG8_LDB(dst, b, h) do { _Pragma("unroll") for (int n = 0; n < 2; ++n) _Pragma("unroll") for (int k = 0; k < 2; ++k) dst[n][k] = *(const PG8_LAS bf16x8*)(lds + PG8_SB(b, h) + boff + n * 2048 + k * 1024); } while (0)
; #define PG8_MMA(ai, bj, At, Bt) do { __builtin_amdgcn_s_setprio(1); _Pragma("unroll") for (int m = 0; m < 4; ++m) _Pragma("unroll") for (int n = 0; n < 2; ++n) _Pragma("unroll") for (int k = 0; k < 2; ++k) \
;         acc[ai][bj][m][n] = __builtin_amdgcn_mfma_f32_16x16x32_bf16(Bt[n][k], At[m][k], acc[ai][bj][m][n], 0, 0, 0); __builtin_amdgcn_s_setprio(0); } while (0)
; #define PG8_WAIT_V(n) asm volatile("s_waitcnt vmcnt(" #n ")" ::: "memory")
; #define PG8_WAIT_L(n) asm volatile("s_waitcnt lgkmcnt(" #n ")" ::: "memory")
; template <class Epi, class Sched, bool ALIGN_EPI = false, bool SP2 = false>
; __device__ __forceinline__ void gemm_phase(PG8_LAS unsigned char* lds, const Gemm g, const Sched& S, const Epi& E) {
;     ...
;             const bool last = (t == nt - 2);
;             const char* a1 = cA + (size_t)(t + 1) * kstep;
;             const char* a2 = last ? nA : cA + (size_t)(t + 2) * kstep; const char* b2 = last ? nB : cB + (size_t)(t + 2) * kstep;
;             const char* a3 = a2 + kstep; const char* b3 = b2 + kstep;
;             if (last && has_next) S.a_ready(nxt);
;             if constexpr (SP2) {
;             PG8_LDB(B0, 0, 0); PG8_LDB(B1, 0, 1); PG8_SCHED; PG8_LDA(At, 0, 0); PG8_STAGE(PG8_SA(1, 1), a1 + hstep, voffA);
;             PG8_WAIT_V(8); PG8_WAIT_L(0); PG8_BAR; PG8_MMA(0, 0, At, B0); PG8_MMA(0, 1, At, B1); PG8_BAR; PG8_SCHED;
;             PG8_LDA(At, 0, 1); PG8_STAGE(PG8_SB(0, 0), b2, voffB); PG8_STAGE(PG8_SB(0, 1), b2 + hstep, voffB); PG8_STAGE(PG8_SA(0, 0), a2, voffA);
;             PG8_WAIT_V(8); PG8_WAIT_L(0); PG8_BAR; PG8_MMA(1, 0, At, B0); PG8_MMA(1, 1, At, B1); PG8_BAR; PG8_SCHED;
.LBB0_1497:
	s_add_u32 s50, s0, 0xfff80080
	s_addc_u32 s51, s1, -1
	s_add_i32 s81, 0, 0x10000
	s_cmp_eq_u32 s80, 28
	s_cselect_b32 s53, s24, s51
	s_cselect_b32 s52, s25, s50
	s_cselect_b32 s51, s43, s75
	s_cselect_b32 s50, s45, s74
	s_add_i32 s84, 0, 0x14000
	v_add_u32_e32 v152, s81, v160
	v_add_u32_e32 v156, s84, v160
	ds_read_b128 v[140:143], v152
	ds_read_b128 v[144:147], v152 offset:1024
	ds_read_b128 v[148:151], v152 offset:2048
	ds_read_b128 v[152:155], v152 offset:3072
	ds_read_b128 v[164:167], v156
	ds_read_b128 v[180:183], v156 offset:1024
	ds_read_b128 v[184:187], v156 offset:2048
	ds_read_b128 v[190:193], v156 offset:3072
	v_lshl_add_u64 v[156:157], s[0:1], 0, v[136:137]
	s_add_i32 m0, s39, 0xc000
	ds_read_b128 v[194:197], v162
	ds_read_b128 v[198:201], v162 offset:1024
	ds_read_b128 v[202:205], v162 offset:2048
	ds_read_b128 v[206:209], v162 offset:3072
	ds_read_b128 v[210:213], v162 offset:4096
	ds_read_b128 v[214:217], v162 offset:5120
	ds_read_b128 v[218:221], v162 offset:6144
	ds_read_b128 v[232:235], v162 offset:7168
	global_load_lds_dwordx4 v[156:157], off
	v_lshl_add_u64 v[156:157], s[0:1], 0, v[138:139]
	s_add_i32 m0, s39, 0xe000
	s_nop 0
	global_load_lds_dwordx4 v[156:157], off
	s_waitcnt vmcnt(8)
	s_waitcnt lgkmcnt(0)
	s_barrier
	s_setprio 1
	s_waitcnt lgkmcnt(0)
	v_mfma_f32_16x16x32_bf16 v[126:129], v[140:143], v[194:197], v[126:129]
	v_mfma_f32_16x16x32_bf16 v[122:125], v[148:151], v[194:197], v[122:125]
	v_mfma_f32_16x16x32_bf16 v[110:113], v[140:143], v[202:205], v[110:113]
	v_mfma_f32_16x16x32_bf16 v[106:109], v[148:151], v[202:205], v[106:109]
	v_mfma_f32_16x16x32_bf16 v[94:97], v[140:143], v[210:213], v[94:97]
	v_mfma_f32_16x16x32_bf16 v[90:93], v[148:151], v[210:213], v[90:93]
	v_mfma_f32_16x16x32_bf16 v[78:81], v[140:143], v[218:221], v[78:81]
	v_mfma_f32_16x16x32_bf16 v[74:77], v[148:151], v[218:221], v[74:77]
	v_mfma_f32_16x16x32_bf16 v[126:129], v[144:147], v[198:201], v[126:129]
	v_mfma_f32_16x16x32_bf16 v[122:125], v[152:155], v[198:201], v[122:125]
	v_mfma_f32_16x16x32_bf16 v[110:113], v[144:147], v[206:209], v[110:113]
	v_mfma_f32_16x16x32_bf16 v[106:109], v[152:155], v[206:209], v[106:109]
	v_mfma_f32_16x16x32_bf16 v[94:97], v[144:147], v[214:217], v[94:97]
	v_mfma_f32_16x16x32_bf16 v[90:93], v[152:155], v[214:217], v[90:93]
	v_mfma_f32_16x16x32_bf16 v[78:81], v[144:147], v[232:235], v[78:81]
	v_mfma_f32_16x16x32_bf16 v[74:77], v[152:155], v[232:235], v[74:77]
	v_mfma_f32_16x16x32_bf16 v[118:121], v[164:167], v[194:197], v[118:121]
	v_mfma_f32_16x16x32_bf16 v[114:117], v[184:187], v[194:197], v[114:117]
	v_mfma_f32_16x16x32_bf16 v[102:105], v[164:167], v[202:205], v[102:105]
	v_mfma_f32_16x16x32_bf16 v[98:101], v[184:187], v[202:205], v[98:101]
	v_mfma_f32_16x16x32_bf16 v[86:89], v[164:167], v[210:213], v[86:89]
	v_mfma_f32_16x16x32_bf16 v[82:85], v[184:187], v[210:213], v[82:85]
	v_mfma_f32_16x16x32_bf16 v[70:73], v[164:167], v[218:221], v[70:73]
	v_mfma_f32_16x16x32_bf16 v[66:69], v[184:187], v[218:221], v[66:69]
	v_mfma_f32_16x16x32_bf16 v[118:121], v[180:183], v[198:201], v[118:121]
	v_mfma_f32_16x16x32_bf16 v[114:117], v[190:193], v[198:201], v[114:117]
	v_mfma_f32_16x16x32_bf16 v[102:105], v[180:183], v[206:209], v[102:105]
	v_mfma_f32_16x16x32_bf16 v[98:101], v[190:193], v[206:209], v[98:101]
	v_mfma_f32_16x16x32_bf16 v[86:89], v[180:183], v[214:217], v[86:89]
	v_mfma_f32_16x16x32_bf16 v[82:85], v[190:193], v[214:217], v[82:85]
	v_mfma_f32_16x16x32_bf16 v[70:73], v[180:183], v[232:235], v[70:73]
	v_mfma_f32_16x16x32_bf16 v[66:69], v[190:193], v[232:235], v[66:69]
	s_setprio 0
	s_barrier
	s_add_i32 s81, s81, s38
	v_lshl_add_u64 v[156:157], s[50:51], 0, v[0:1]
	s_mov_b32 m0, s81
	ds_read_b128 v[194:197], v162 offset:16384
	ds_read_b128 v[198:201], v162 offset:17408
	ds_read_b128 v[202:205], v162 offset:18432
	ds_read_b128 v[206:209], v162 offset:19456
	ds_read_b128 v[210:213], v162 offset:20480
	ds_read_b128 v[214:217], v162 offset:21504
	ds_read_b128 v[218:221], v162 offset:22528
	ds_read_b128 v[232:235], v162 offset:23552
	global_load_lds_dwordx4 v[156:157], off
	s_add_i32 m0, s81, 0x2000
	s_add_u32 s82, s50, 0x80000
	v_lshl_add_u64 v[168:169], s[50:51], 0, v[130:131]
	s_addc_u32 s83, s51, 0
	s_add_i32 s81, s84, s38
	global_load_lds_dwordx4 v[168:169], off
	v_lshl_add_u64 v[222:223], s[82:83], 0, v[0:1]
	s_mov_b32 m0, s81
	v_lshl_add_u64 v[236:237], s[52:53], 0, v[132:133]
	global_load_lds_dwordx4 v[222:223], off
	v_lshl_add_u64 v[222:223], s[82:83], 0, v[130:131]
	s_add_i32 m0, s81, 0x2000
	s_nop 0
	global_load_lds_dwordx4 v[222:223], off
	v_lshl_add_u64 v[222:223], s[52:53], 0, v[134:135]
	s_mov_b32 m0, s39
	s_nop 0
	global_load_lds_dwordx4 v[222:223], off
	s_mov_b32 m0, s58
	s_nop 0
	global_load_lds_dwordx4 v[236:237], off
	s_waitcnt vmcnt(8)
	s_waitcnt lgkmcnt(0)
	s_barrier
; #define PG8_STAGE(bufoff, gbase, voff) do { _Pragma("unroll") for (int _i = 0; _i < 2; ++_i) \
;         __builtin_amdgcn_global_load_lds((const unsigned*)((const char*)(gbase) + (voff)[_i]), (PG8_LAS unsigned*)(lds + (bufoff) + ldsw + _i * 8192), 16, 0, 0); } while (0)
; #define PG8_LDA(dst, b, h) do { _Pragma("unroll") for (int m = 0; m < 4; ++m) _Pragma("unroll") for (int k = 0; k < 2; ++k) dst[m][k] = *(const PG8_LAS bf16x8*)(lds + PG8_SA(b, h) + aoff + m * 2048 + k * 1024); } while (0)
; #define PG8_LDB(dst, b, h) do { _Pragma("unroll") for (int n = 0; n < 2; ++n) _Pragma("unroll") for (int k = 0; k < 2; ++k) dst[n][k] = *(const PG8_LAS bf16x8*)(lds + PG8_SB(b, h) + boff + n * 2048 + k * 1024); } while (0)
; #define PG8_MMA(ai, bj, At, Bt) do { __builtin_amdgcn_s_setprio(1); _Pragma("unroll") for (int m = 0; m < 4; ++m) _Pragma("unroll") for (int n = 0; n < 2; ++n) _Pragma("unroll") for (int k = 0; k < 2; ++k) \
;         acc[ai][bj][m][n] = __builtin_amdgcn_mfma_f32_16x16x32_bf16(Bt[n][k], At[m][k], acc[ai][bj][m][n], 0, 0, 0); __builtin_amdgcn_s_setprio(0); } while (0)
; #define PG8_WAIT_V(n) asm volatile("s_waitcnt vmcnt(" #n ")" ::: "memory")
; #define PG8_WAIT_L(n) asm volatile("s_waitcnt lgkmcnt(" #n ")" ::: "memory")
; #define PG8_BAR __builtin_amdgcn_s_barrier()
; #define PG8_SCHED __builtin_amdgcn_sched_barrier(0)
; template <class Epi, class Sched, bool ALIGN_EPI = false, bool SP2 = false>
; __device__ __forceinline__ void gemm_phase(PG8_LAS unsigned char* lds, const Gemm g, const Sched& S, const Epi& E) {
;     ...
;             PG8_WAIT_V(8); PG8_WAIT_L(0); PG8_BAR; PG8_MMA(1, 0, At, B0); PG8_MMA(1, 1, At, B1); PG8_BAR; PG8_SCHED;
;             PG8_LDB(B0, 1, 0); PG8_LDB(B1, 1, 1); PG8_SCHED; PG8_LDA(At, 1, 0); PG8_STAGE(PG8_SA(0, 1), a2 + hstep, voffA);
;             PG8_WAIT_V(8); PG8_WAIT_L(0); PG8_BAR; PG8_MMA(0, 0, At, B0); PG8_MMA(0, 1, At, B1); PG8_BAR; PG8_SCHED;
;             PG8_LDA(At, 1, 1); PG8_STAGE(PG8_SB(1, 0), b3, voffB); PG8_STAGE(PG8_SB(1, 1), b3 + hstep, voffB); PG8_STAGE(PG8_SA(1, 0), a3, voffA);
	s_setprio 1
	s_waitcnt lgkmcnt(0)
	v_mfma_f32_16x16x32_bf16 v[62:65], v[140:143], v[194:197], v[62:65]
	v_mfma_f32_16x16x32_bf16 v[58:61], v[148:151], v[194:197], v[58:61]
	v_mfma_f32_16x16x32_bf16 v[46:49], v[140:143], v[202:205], v[46:49]
	v_mfma_f32_16x16x32_bf16 v[42:45], v[148:151], v[202:205], v[42:45]
	v_mfma_f32_16x16x32_bf16 v[30:33], v[140:143], v[210:213], v[30:33]
	v_mfma_f32_16x16x32_bf16 v[26:29], v[148:151], v[210:213], v[26:29]
	v_mfma_f32_16x16x32_bf16 v[14:17], v[140:143], v[218:221], v[14:17]
	v_mfma_f32_16x16x32_bf16 v[10:13], v[148:151], v[218:221], v[10:13]
	v_mfma_f32_16x16x32_bf16 v[62:65], v[144:147], v[198:201], v[62:65]
	v_mfma_f32_16x16x32_bf16 v[58:61], v[152:155], v[198:201], v[58:61]
	v_mfma_f32_16x16x32_bf16 v[46:49], v[144:147], v[206:209], v[46:49]
	v_mfma_f32_16x16x32_bf16 v[42:45], v[152:155], v[206:209], v[42:45]
	v_mfma_f32_16x16x32_bf16 v[30:33], v[144:147], v[214:217], v[30:33]
	v_mfma_f32_16x16x32_bf16 v[26:29], v[152:155], v[214:217], v[26:29]
	v_mfma_f32_16x16x32_bf16 v[14:17], v[144:147], v[232:235], v[14:17]
	v_mfma_f32_16x16x32_bf16 v[10:13], v[152:155], v[232:235], v[10:13]
	v_mfma_f32_16x16x32_bf16 v[54:57], v[164:167], v[194:197], v[54:57]
	v_mfma_f32_16x16x32_bf16 v[50:53], v[184:187], v[194:197], v[50:53]
	v_mfma_f32_16x16x32_bf16 v[38:41], v[164:167], v[202:205], v[38:41]
	v_mfma_f32_16x16x32_bf16 v[34:37], v[184:187], v[202:205], v[34:37]
	v_mfma_f32_16x16x32_bf16 v[22:25], v[164:167], v[210:213], v[22:25]
	v_mfma_f32_16x16x32_bf16 v[18:21], v[184:187], v[210:213], v[18:21]
	v_mfma_f32_16x16x32_bf16 v[6:9], v[164:167], v[218:221], v[6:9]
	v_mfma_f32_16x16x32_bf16 v[2:5], v[184:187], v[218:221], v[2:5]
	v_mfma_f32_16x16x32_bf16 v[54:57], v[180:183], v[198:201], v[54:57]
	v_mfma_f32_16x16x32_bf16 v[50:53], v[190:193], v[198:201], v[50:53]
	v_mfma_f32_16x16x32_bf16 v[38:41], v[180:183], v[206:209], v[38:41]
	v_mfma_f32_16x16x32_bf16 v[34:37], v[190:193], v[206:209], v[34:37]
	v_mfma_f32_16x16x32_bf16 v[22:25], v[180:183], v[214:217], v[22:25]
	v_mfma_f32_16x16x32_bf16 v[18:21], v[190:193], v[214:217], v[18:21]
	v_mfma_f32_16x16x32_bf16 v[6:9], v[180:183], v[232:235], v[6:9]
	v_mfma_f32_16x16x32_bf16 v[2:5], v[190:193], v[232:235], v[2:5]
	s_setprio 0
	s_barrier
	s_add_i32 s81, 0, 0x18000
	s_add_i32 s82, 0, 0x1c000
	v_add_u32_e32 v152, s81, v160
	v_add_u32_e32 v158, s82, v160
	ds_read_b128 v[140:143], v152
	ds_read_b128 v[144:147], v152 offset:1024
	ds_read_b128 v[148:151], v152 offset:2048
	ds_read_b128 v[152:155], v152 offset:3072
	ds_read_b128 v[164:167], v158
	ds_read_b128 v[180:183], v158 offset:1024
	ds_read_b128 v[184:187], v158 offset:2048
	ds_read_b128 v[190:193], v158 offset:3072
	s_add_u32 s52, s52, 0x80000
	s_addc_u32 s53, s53, 0
	s_mov_b32 m0, s60
	v_lshl_add_u64 v[238:239], s[52:53], 0, v[134:135]
	ds_read_b128 v[194:197], v162 offset:32768
	ds_read_b128 v[198:201], v162 offset:33792
	ds_read_b128 v[202:205], v162 offset:34816
	ds_read_b128 v[206:209], v162 offset:35840
	ds_read_b128 v[210:213], v162 offset:36864
	ds_read_b128 v[214:217], v162 offset:37888
	ds_read_b128 v[218:221], v162 offset:38912
	ds_read_b128 v[232:235], v162 offset:39936
	global_load_lds_dwordx4 v[238:239], off
	v_lshl_add_u64 v[238:239], s[52:53], 0, v[132:133]
	s_mov_b32 m0, s61
	s_nop 0
	global_load_lds_dwordx4 v[238:239], off
	s_waitcnt vmcnt(8)
	s_waitcnt lgkmcnt(0)
	s_barrier
	s_setprio 1
	s_waitcnt lgkmcnt(0)
	v_mfma_f32_16x16x32_bf16 v[126:129], v[140:143], v[194:197], v[126:129]
	v_mfma_f32_16x16x32_bf16 v[122:125], v[148:151], v[194:197], v[122:125]
	v_mfma_f32_16x16x32_bf16 v[110:113], v[140:143], v[202:205], v[110:113]
	v_mfma_f32_16x16x32_bf16 v[106:109], v[148:151], v[202:205], v[106:109]
	v_mfma_f32_16x16x32_bf16 v[94:97], v[140:143], v[210:213], v[94:97]
	v_mfma_f32_16x16x32_bf16 v[90:93], v[148:151], v[210:213], v[90:93]
	v_mfma_f32_16x16x32_bf16 v[78:81], v[140:143], v[218:221], v[78:81]
	v_mfma_f32_16x16x32_bf16 v[74:77], v[148:151], v[218:221], v[74:77]
	v_mfma_f32_16x16x32_bf16 v[126:129], v[144:147], v[198:201], v[126:129]
	v_mfma_f32_16x16x32_bf16 v[122:125], v[152:155], v[198:201], v[122:125]
	v_mfma_f32_16x16x32_bf16 v[110:113], v[144:147], v[206:209], v[110:113]
	v_mfma_f32_16x16x32_bf16 v[106:109], v[152:155], v[206:209], v[106:109]
	v_mfma_f32_16x16x32_bf16 v[94:97], v[144:147], v[214:217], v[94:97]
	v_mfma_f32_16x16x32_bf16 v[90:93], v[152:155], v[214:217], v[90:93]
	v_mfma_f32_16x16x32_bf16 v[78:81], v[144:147], v[232:235], v[78:81]
	v_mfma_f32_16x16x32_bf16 v[74:77], v[152:155], v[232:235], v[74:77]
	v_mfma_f32_16x16x32_bf16 v[118:121], v[164:167], v[194:197], v[118:121]
	v_mfma_f32_16x16x32_bf16 v[114:117], v[184:187], v[194:197], v[114:117]
	v_mfma_f32_16x16x32_bf16 v[102:105], v[164:167], v[202:205], v[102:105]
	v_mfma_f32_16x16x32_bf16 v[98:101], v[184:187], v[202:205], v[98:101]
	v_mfma_f32_16x16x32_bf16 v[86:89], v[164:167], v[210:213], v[86:89]
	v_mfma_f32_16x16x32_bf16 v[82:85], v[184:187], v[210:213], v[82:85]
	v_mfma_f32_16x16x32_bf16 v[70:73], v[164:167], v[218:221], v[70:73]
	v_mfma_f32_16x16x32_bf16 v[66:69], v[184:187], v[218:221], v[66:69]
	v_mfma_f32_16x16x32_bf16 v[118:121], v[180:183], v[198:201], v[118:121]
	v_mfma_f32_16x16x32_bf16 v[114:117], v[190:193], v[198:201], v[114:117]
	v_mfma_f32_16x16x32_bf16 v[102:105], v[180:183], v[206:209], v[102:105]
	v_mfma_f32_16x16x32_bf16 v[98:101], v[190:193], v[206:209], v[98:101]
	v_mfma_f32_16x16x32_bf16 v[86:89], v[180:183], v[214:217], v[86:89]
	v_mfma_f32_16x16x32_bf16 v[82:85], v[190:193], v[214:217], v[82:85]
	v_mfma_f32_16x16x32_bf16 v[70:73], v[180:183], v[232:235], v[70:73]
	v_mfma_f32_16x16x32_bf16 v[66:69], v[190:193], v[232:235], v[66:69]
	s_setprio 0
	s_barrier
; #define PG8_STAGE(bufoff, gbase, voff) do { _Pragma("unroll") for (int _i = 0; _i < 2; ++_i) \
;         __builtin_amdgcn_global_load_lds((const unsigned*)((const char*)(gbase) + (voff)[_i]), (PG8_LAS unsigned*)(lds + (bufoff) + ldsw + _i * 8192), 16, 0, 0); } while (0)
; #define PG8_LDA(dst, b, h) do { _Pragma("unroll") for (int m = 0; m < 4; ++m) _Pragma("unroll") for (int k = 0; k < 2; ++k) dst[m][k] = *(const PG8_LAS bf16x8*)(lds + PG8_SA(b, h) + aoff + m * 2048 + k * 1024); } while (0)
; #define PG8_MMA(ai, bj, At, Bt) do { __builtin_amdgcn_s_setprio(1); _Pragma("unroll") for (int m = 0; m < 4; ++m) _Pragma("unroll") for (int n = 0; n < 2; ++n) _Pragma("unroll") for (int k = 0; k < 2; ++k) \
;         acc[ai][bj][m][n] = __builtin_amdgcn_mfma_f32_16x16x32_bf16(Bt[n][k], At[m][k], acc[ai][bj][m][n], 0, 0, 0); __builtin_amdgcn_s_setprio(0); } while (0)
; #define PG8_WAIT_V(n) asm volatile("s_waitcnt vmcnt(" #n ")" ::: "memory")
; #define PG8_WAIT_L(n) asm volatile("s_waitcnt lgkmcnt(" #n ")" ::: "memory")
; #define PG8_BAR __builtin_amdgcn_s_barrier()
; #define PG8_SCHED __builtin_amdgcn_sched_barrier(0)
; template <class Epi, class Sched, bool ALIGN_EPI = false, bool SP2 = false>
; __device__ __forceinline__ void gemm_phase(PG8_LAS unsigned char* lds, const Gemm g, const Sched& S, const Epi& E) {
;     ...
;             PG8_LDA(At, 1, 1); PG8_STAGE(PG8_SB(1, 0), b3, voffB); PG8_STAGE(PG8_SB(1, 1), b3 + hstep, voffB); PG8_STAGE(PG8_SA(1, 0), a3, voffA);
;             PG8_WAIT_V(8); PG8_WAIT_L(0); PG8_BAR; PG8_MMA(1, 0, At, B0); PG8_MMA(1, 1, At, B1); PG8_BAR; PG8_SCHED;
;     ...
;         if constexpr (ALIGN_EPI) { if (wr == 0) PG8_BAR; }
	s_add_i32 s52, s81, s38
	v_lshl_add_u64 v[156:157], v[156:157], 0, s[12:13]
	s_mov_b32 m0, s52
	ds_read_b128 v[194:197], v162 offset:49152
	ds_read_b128 v[198:201], v162 offset:50176
	ds_read_b128 v[202:205], v162 offset:51200
	ds_read_b128 v[206:209], v162 offset:52224
	ds_read_b128 v[210:213], v162 offset:53248
	ds_read_b128 v[214:217], v162 offset:54272
	ds_read_b128 v[218:221], v162 offset:55296
	ds_read_b128 v[232:235], v162 offset:56320
	global_load_lds_dwordx4 v[156:157], off
	s_add_i32 m0, s52, 0x2000
	s_add_u32 s50, s50, 0x80080
	v_lshl_add_u64 v[156:157], v[168:169], 0, s[12:13]
	s_addc_u32 s51, s51, 0
	s_add_i32 s52, s82, s38
	global_load_lds_dwordx4 v[156:157], off
	v_lshl_add_u64 v[156:157], s[50:51], 0, v[0:1]
	s_mov_b32 m0, s52
	s_nop 0
	global_load_lds_dwordx4 v[156:157], off
	v_lshl_add_u64 v[156:157], s[50:51], 0, v[130:131]
	s_add_i32 m0, s52, 0x2000
	s_nop 0
	global_load_lds_dwordx4 v[156:157], off
	v_lshl_add_u64 v[156:157], v[222:223], 0, s[12:13]
	s_mov_b32 m0, s62
	s_nop 0
	global_load_lds_dwordx4 v[156:157], off
	v_lshl_add_u64 v[156:157], v[236:237], 0, s[12:13]
	s_mov_b32 m0, s63
	s_nop 0
	global_load_lds_dwordx4 v[156:157], off
	s_waitcnt vmcnt(8)
	s_waitcnt lgkmcnt(0)
	s_barrier
	s_setprio 1
	s_waitcnt lgkmcnt(0)
	v_mfma_f32_16x16x32_bf16 v[62:65], v[140:143], v[194:197], v[62:65]
	v_mfma_f32_16x16x32_bf16 v[58:61], v[148:151], v[194:197], v[58:61]
	v_mfma_f32_16x16x32_bf16 v[46:49], v[140:143], v[202:205], v[46:49]
	v_mfma_f32_16x16x32_bf16 v[42:45], v[148:151], v[202:205], v[42:45]
	v_mfma_f32_16x16x32_bf16 v[30:33], v[140:143], v[210:213], v[30:33]
	v_mfma_f32_16x16x32_bf16 v[26:29], v[148:151], v[210:213], v[26:29]
	v_mfma_f32_16x16x32_bf16 v[14:17], v[140:143], v[218:221], v[14:17]
	v_mfma_f32_16x16x32_bf16 v[10:13], v[148:151], v[218:221], v[10:13]
	v_mfma_f32_16x16x32_bf16 v[62:65], v[144:147], v[198:201], v[62:65]
	v_mfma_f32_16x16x32_bf16 v[58:61], v[152:155], v[198:201], v[58:61]
	v_mfma_f32_16x16x32_bf16 v[46:49], v[144:147], v[206:209], v[46:49]
	v_mfma_f32_16x16x32_bf16 v[42:45], v[152:155], v[206:209], v[42:45]
	v_mfma_f32_16x16x32_bf16 v[30:33], v[144:147], v[214:217], v[30:33]
	v_mfma_f32_16x16x32_bf16 v[26:29], v[152:155], v[214:217], v[26:29]
	v_mfma_f32_16x16x32_bf16 v[14:17], v[144:147], v[232:235], v[14:17]
	v_mfma_f32_16x16x32_bf16 v[10:13], v[152:155], v[232:235], v[10:13]
	v_mfma_f32_16x16x32_bf16 v[54:57], v[164:167], v[194:197], v[54:57]
	v_mfma_f32_16x16x32_bf16 v[50:53], v[184:187], v[194:197], v[50:53]
	v_mfma_f32_16x16x32_bf16 v[38:41], v[164:167], v[202:205], v[38:41]
	v_mfma_f32_16x16x32_bf16 v[34:37], v[184:187], v[202:205], v[34:37]
	v_mfma_f32_16x16x32_bf16 v[22:25], v[164:167], v[210:213], v[22:25]
	v_mfma_f32_16x16x32_bf16 v[18:21], v[184:187], v[210:213], v[18:21]
	v_mfma_f32_16x16x32_bf16 v[6:9], v[164:167], v[218:221], v[6:9]
	v_mfma_f32_16x16x32_bf16 v[2:5], v[184:187], v[218:221], v[2:5]
	v_mfma_f32_16x16x32_bf16 v[54:57], v[180:183], v[198:201], v[54:57]
	v_mfma_f32_16x16x32_bf16 v[50:53], v[190:193], v[198:201], v[50:53]
	v_mfma_f32_16x16x32_bf16 v[38:41], v[180:183], v[206:209], v[38:41]
	v_mfma_f32_16x16x32_bf16 v[34:37], v[190:193], v[206:209], v[34:37]
	v_mfma_f32_16x16x32_bf16 v[22:25], v[180:183], v[214:217], v[22:25]
	v_mfma_f32_16x16x32_bf16 v[18:21], v[190:193], v[214:217], v[18:21]
	v_mfma_f32_16x16x32_bf16 v[6:9], v[180:183], v[232:235], v[6:9]
	v_mfma_f32_16x16x32_bf16 v[2:5], v[190:193], v[232:235], v[2:5]
	s_setprio 0
	s_barrier
	s_add_i32 s80, s80, 2
	s_add_u32 s0, s0, 0x100
	s_addc_u32 s1, s1, 0
	s_add_u32 s74, s74, 0x100
	s_addc_u32 s75, s75, 0
	s_cmp_gt_u32 s80, 29
	s_cbranch_scc0 .LBB0_1497
	s_and_b64 vcc, exec, s[30:31]
	s_cbranch_vccz .LBB0_1500
	s_barrier
